# final scan pass: the 56 serialized wcomp LDS reads of the cross-wave carry chain prefetched per channel block (14 at a time) instead of read+wait per step; plus static prio waves 0-3 in GEMM loops and
# speedup vs baseline: 1.0199x; 1.0016x over previous
; __device__ __forceinline__ void scan_group(const Params& P, int l, int wgI, bool final_mode, bool with_ctx, LAS unsigned char* lds) {
;     ...
; #pragma unroll
;             for (int eb = 0; eb < 4; ++eb) {
;                 const int c = eb * 16 + fr;
;                 float s = car[(0 * 9 + it) * 64 + c];
; #pragma unroll
;                 for (int v = 0; v < 7; ++v) { const f32x2 cv = wcomp[(0 * 8 + v) * 64 + c]; if (v < w) s = cv.x * s + cv.y; }
;                 s = Ae[0][eb] * s + Be[0][eb];
.LBB0_306:
	s_waitcnt lgkmcnt(0)
	s_barrier
	ds_read_b64 v[150:151], v50 offset:42752
	ds_read_b64 v[152:153], v50 offset:43264
	ds_read_b64 v[154:155], v50 offset:43776
	ds_read_b64 v[156:157], v50 offset:44288
	ds_read_b64 v[158:159], v50 offset:44800
	ds_read_b64 v[160:161], v50 offset:45312
	ds_read_b64 v[162:163], v50 offset:45824
	ds_read_b64 v[164:165], v50 offset:50432
	ds_read_b64 v[166:167], v50 offset:49920
	ds_read_b64 v[168:169], v50 offset:49408
	ds_read_b64 v[170:171], v50 offset:48896
	ds_read_b64 v[172:173], v50 offset:48384
	ds_read_b64 v[174:175], v50 offset:47872
	ds_read_b64 v[176:177], v50 offset:47360
	ds_read_b32 v46, v55
	v_cndmask_b32_e64 v47, 0, 1, s[0:1]
	v_cmp_ne_u32_e64 s[48:49], 1, v47
	s_andn2_b64 vcc, exec, s[0:1]
	s_cbranch_vccnz .LBB0_308
	s_waitcnt lgkmcnt(0)
	v_fmac_f32_e32 v151, v46, v150
	v_mov_b32_e32 v46, v151

; __device__ __forceinline__ void scan_group(const Params& P, int l, int wgI, bool final_mode, bool with_ctx, LAS unsigned char* lds) {
;     ...
; #pragma unroll
;                 for (int v = 0; v < 7; ++v) { const f32x2 cv = wcomp[(0 * 8 + v) * 64 + c]; if (v < w) s = cv.x * s + cv.y; }
.LBB0_314:
	s_waitcnt lgkmcnt(0)
	v_fmac_f32_e32 v163, v46, v162
	v_mov_b32_e32 v46, v163

; #define LAS __attribute__((address_space(3)))
; __device__ __forceinline__ unsigned pk2(float lo, float hi) { unsigned r; asm("v_cvt_pk_bf16_f32 %0, %1, %2" : "=v"(r) : "v"(lo), "v"(hi)); return r; }
; __device__ __forceinline__ float bflo(unsigned w) { return __uint_as_float(w << 16); }
; __device__ __forceinline__ float sigmoidf_(float v) { return __builtin_amdgcn_rcpf(1.0f + __expf(-v)); }
; __device__ __forceinline__ void scan_group(const Params& P, int l, int wgI, bool final_mode, bool with_ctx, LAS unsigned char* lds) {
;     ...
;             for (int eb = 0; eb < 4; ++eb) {
;                 const int c = eb * 16 + fr;
;                 float s = car[(0 * 9 + it) * 64 + c];
; #pragma unroll
;                 for (int v = 0; v < 7; ++v) { const f32x2 cv = wcomp[(0 * 8 + v) * 64 + c]; if (v < w) s = cv.x * s + cv.y; }
;                 s = Ae[0][eb] * s + Be[0][eb];
;                 float hf[4];
; #pragma unroll
;                 for (int j = 0; j < 4; ++j) { s = ca[0][eb][j] * s + cbv[0][eb][j]; hf[j] = s; }
;                 s = car[(1 * 9 + it) * 64 + c];
; #pragma unroll
;                 for (int v = 7; v > 0; --v) { const f32x2 cv = wcomp[(1 * 8 + v) * 64 + c]; if (v > w) s = cv.x * s + cv.y; }
;                 s = Ae[1][eb] * s + Be[1][eb];
; #pragma unroll
;                 for (int j = 3; j >= 0; --j) { s = ca[1][eb][j] * s + cbv[1][eb][j]; hf[j] += s; }
; #pragma unroll
;                 for (int j = 0; j < 4; ++j) {
;                     const int q = 16 * w + 4 * fq + j;
;                     const float g = bflo((unsigned)*(const LAS bf16_t*)(lds + SC_GL_OFF + q * 128 + c * 2));
;                     const float ge = g * sigmoidf_(1.5957691216f * (g + 0.044715f * g * g * g));
;                     *(LAS bf16_t*)(lds + SC_XC_OFF + q * 128 + c * 2) = (bf16_t)(pk2(hf[j] * ge, 0.f) & 0xffffu);
;                 }
.LBB0_322:
	ds_read_b64 v[150:151], v50 offset:42880
	ds_read_b64 v[152:153], v50 offset:43392
	ds_read_b64 v[154:155], v50 offset:43904
	ds_read_b64 v[156:157], v50 offset:44416
	ds_read_b64 v[158:159], v50 offset:44928
	ds_read_b64 v[160:161], v50 offset:45440
	ds_read_b64 v[162:163], v50 offset:45952
	ds_read_b64 v[164:165], v50 offset:50560
	ds_read_b64 v[166:167], v50 offset:50048
	ds_read_b64 v[168:169], v50 offset:49536
	ds_read_b64 v[170:171], v50 offset:49024
	ds_read_b64 v[172:173], v50 offset:48512
	ds_read_b64 v[174:175], v50 offset:48000
	ds_read_b64 v[176:177], v50 offset:47488
	v_cndmask_b32_e64 v135, v135, 1.0, s[44:45]
	v_cndmask_b32_e64 v136, v136, 0, s[44:45]
	s_waitcnt lgkmcnt(1)
	v_fmac_f32_e32 v136, v135, v46
	v_fmac_f32_e32 v123, v131, v136
	v_cndmask_b32_e64 v46, v145, 1.0, s[40:41]
	v_cndmask_b32_e64 v131, v146, 0, s[40:41]
	s_waitcnt lgkmcnt(0)
	v_fmac_f32_e32 v131, v46, v47
	v_fmac_f32_e32 v125, v132, v123
	v_fmac_f32_e32 v144, v143, v131
	v_fmac_f32_e32 v129, v133, v125
	v_fmac_f32_e32 v141, v142, v144
	v_fmac_f32_e32 v130, v134, v129
	v_add_f32_e32 v46, v129, v141
	ds_read_u16 v129, v57
	v_add_f32_e32 v47, v130, v144
	ds_read_u16 v130, v57 offset:128
	ds_read_u16 v131, v57 offset:256
	ds_read_u16 v132, v57 offset:384
	v_fmac_f32_e32 v139, v140, v141
	v_fmac_f32_e32 v138, v137, v139
	s_waitcnt lgkmcnt(3)
	v_lshlrev_b32_e32 v129, 16, v129
	v_mul_f32_e32 v133, 0x3d372713, v129
	v_mul_f32_e32 v133, v133, v129
	v_fma_f32 v133, v133, v129, v129
	v_mul_f32_e32 v133, 0x3fcc422a, v133
	v_mul_f32_e32 v133, 0xbfb8aa3b, v133
	v_exp_f32_e32 v133, v133
	s_waitcnt lgkmcnt(2)
	v_lshlrev_b32_e32 v130, 16, v130
	v_mul_f32_e32 v134, 0x3d372713, v130
	v_mul_f32_e32 v134, v134, v130
	v_fma_f32 v134, v134, v130, v130
	v_add_f32_e32 v133, 1.0, v133
	v_mul_f32_e32 v134, 0x3fcc422a, v134
	v_rcp_f32_e32 v133, v133
	v_mul_f32_e32 v134, 0xbfb8aa3b, v134
	v_exp_f32_e32 v134, v134
	v_add_f32_e32 v123, v123, v138
	v_mul_f32_e32 v129, v133, v129
	s_waitcnt lgkmcnt(1)
	v_lshlrev_b32_e32 v131, 16, v131
	v_mul_f32_e32 v123, v123, v129
	v_add_f32_e32 v129, 1.0, v134
	v_mul_f32_e32 v133, 0x3d372713, v131
	v_rcp_f32_e32 v129, v129
	v_mul_f32_e32 v133, v133, v131
	v_fma_f32 v133, v133, v131, v131
	v_mul_f32_e32 v133, 0x3fcc422a, v133
	v_cvt_pk_bf16_f32 v123, v123, v185
	v_mul_f32_e32 v133, 0xbfb8aa3b, v133
	v_exp_f32_e32 v133, v133
	ds_write_b16 v58, v123
	v_mul_f32_e32 v123, v129, v130
	s_waitcnt lgkmcnt(1)
	v_lshlrev_b32_e32 v129, 16, v132
	v_mul_f32_e32 v130, 0x3d372713, v129
	v_mul_f32_e32 v130, v130, v129
	v_add_f32_e32 v125, v125, v139
	v_fma_f32 v130, v130, v129, v129
	v_mul_f32_e32 v123, v125, v123
	v_add_f32_e32 v125, 1.0, v133
	v_mul_f32_e32 v130, 0x3fcc422a, v130
	v_rcp_f32_e32 v125, v125
	v_mul_f32_e32 v130, 0xbfb8aa3b, v130
	v_exp_f32_e32 v130, v130
	v_cvt_pk_bf16_f32 v123, v123, v185
	ds_write_b16 v58, v123 offset:128
	v_mul_f32_e32 v123, v125, v131
	v_add_f32_e32 v125, 1.0, v130
	v_mul_f32_e32 v46, v46, v123
	v_rcp_f32_e32 v125, v125
	v_cvt_pk_bf16_f32 v46, v46, v185
	ds_write_b16 v58, v46 offset:256
	ds_read_b32 v46, v55 offset:64
	v_mul_f32_e32 v123, v125, v129
	v_mul_f32_e32 v47, v47, v123
	s_and_b64 vcc, exec, s[48:49]
	v_cvt_pk_bf16_f32 v47, v47, v185
	ds_write_b16 v58, v47 offset:384
	s_cbranch_vccnz .LBB0_324
	s_waitcnt lgkmcnt(0)
	v_fmac_f32_e32 v151, v46, v150
	v_mov_b32_e32 v46, v151

; #define LAS __attribute__((address_space(3)))
; __device__ __forceinline__ unsigned pk2(float lo, float hi) { unsigned r; asm("v_cvt_pk_bf16_f32 %0, %1, %2" : "=v"(r) : "v"(lo), "v"(hi)); return r; }
; __device__ __forceinline__ float bflo(unsigned w) { return __uint_as_float(w << 16); }
; __device__ __forceinline__ float sigmoidf_(float v) { return __builtin_amdgcn_rcpf(1.0f + __expf(-v)); }
; __device__ __forceinline__ void scan_group(const Params& P, int l, int wgI, bool final_mode, bool with_ctx, LAS unsigned char* lds) {
;     ...
;             for (int eb = 0; eb < 4; ++eb) {
;                 const int c = eb * 16 + fr;
;                 float s = car[(0 * 9 + it) * 64 + c];
; #pragma unroll
;                 for (int v = 0; v < 7; ++v) { const f32x2 cv = wcomp[(0 * 8 + v) * 64 + c]; if (v < w) s = cv.x * s + cv.y; }
;                 s = Ae[0][eb] * s + Be[0][eb];
;                 float hf[4];
; #pragma unroll
;                 for (int j = 0; j < 4; ++j) { s = ca[0][eb][j] * s + cbv[0][eb][j]; hf[j] = s; }
;                 s = car[(1 * 9 + it) * 64 + c];
; #pragma unroll
;                 for (int v = 7; v > 0; --v) { const f32x2 cv = wcomp[(1 * 8 + v) * 64 + c]; if (v > w) s = cv.x * s + cv.y; }
;                 s = Ae[1][eb] * s + Be[1][eb];
; #pragma unroll
;                 for (int j = 3; j >= 0; --j) { s = ca[1][eb][j] * s + cbv[1][eb][j]; hf[j] += s; }
; #pragma unroll
;                 for (int j = 0; j < 4; ++j) {
;                     const int q = 16 * w + 4 * fq + j;
;                     const float g = bflo((unsigned)*(const LAS bf16_t*)(lds + SC_GL_OFF + q * 128 + c * 2));
;                     const float ge = g * sigmoidf_(1.5957691216f * (g + 0.044715f * g * g * g));
;                     *(LAS bf16_t*)(lds + SC_XC_OFF + q * 128 + c * 2) = (bf16_t)(pk2(hf[j] * ge, 0.f) & 0xffffu);
;                 }
.LBB0_337:
	ds_read_b64 v[150:151], v50 offset:43008
	ds_read_b64 v[152:153], v50 offset:43520
	ds_read_b64 v[154:155], v50 offset:44032
	ds_read_b64 v[156:157], v50 offset:44544
	ds_read_b64 v[158:159], v50 offset:45056
	ds_read_b64 v[160:161], v50 offset:45568
	ds_read_b64 v[162:163], v50 offset:46080
	ds_read_b64 v[164:165], v50 offset:50688
	ds_read_b64 v[166:167], v50 offset:50176
	ds_read_b64 v[168:169], v50 offset:49664
	ds_read_b64 v[170:171], v50 offset:49152
	ds_read_b64 v[172:173], v50 offset:48640
	ds_read_b64 v[174:175], v50 offset:48128
	ds_read_b64 v[176:177], v50 offset:47616
	v_cndmask_b32_e64 v115, v115, 1.0, s[44:45]
	v_cndmask_b32_e64 v116, v116, 0, s[44:45]
	s_waitcnt lgkmcnt(2)
	v_fmac_f32_e32 v116, v115, v46
	v_fmac_f32_e32 v105, v111, v116
	v_cndmask_b32_e64 v46, v127, 1.0, s[40:41]
	v_cndmask_b32_e64 v111, v128, 0, s[40:41]
	s_waitcnt lgkmcnt(0)
	v_fmac_f32_e32 v111, v46, v47
	v_fmac_f32_e32 v106, v112, v105
	v_fmac_f32_e32 v126, v124, v111
	v_fmac_f32_e32 v109, v113, v106
	v_fmac_f32_e32 v121, v122, v126
	v_fmac_f32_e32 v110, v114, v109
	v_add_f32_e32 v46, v109, v121
	ds_read_u16 v109, v59
	v_add_f32_e32 v47, v110, v126
	ds_read_u16 v110, v59 offset:128
	ds_read_u16 v111, v59 offset:256
	ds_read_u16 v112, v59 offset:384
	v_fmac_f32_e32 v119, v120, v121
	v_fmac_f32_e32 v118, v117, v119
	s_waitcnt lgkmcnt(3)
	v_lshlrev_b32_e32 v109, 16, v109
	v_mul_f32_e32 v113, 0x3d372713, v109
	v_mul_f32_e32 v113, v113, v109
	v_fma_f32 v113, v113, v109, v109
	v_mul_f32_e32 v113, 0x3fcc422a, v113
	v_mul_f32_e32 v113, 0xbfb8aa3b, v113
	v_exp_f32_e32 v113, v113
	s_waitcnt lgkmcnt(2)
	v_lshlrev_b32_e32 v110, 16, v110
	v_mul_f32_e32 v114, 0x3d372713, v110
	v_mul_f32_e32 v114, v114, v110
	v_fma_f32 v114, v114, v110, v110
	v_add_f32_e32 v113, 1.0, v113
	v_mul_f32_e32 v114, 0x3fcc422a, v114
	v_rcp_f32_e32 v113, v113
	v_mul_f32_e32 v114, 0xbfb8aa3b, v114
	v_exp_f32_e32 v114, v114
	v_add_f32_e32 v105, v105, v118
	v_mul_f32_e32 v109, v113, v109
	s_waitcnt lgkmcnt(1)
	v_lshlrev_b32_e32 v111, 16, v111
	v_mul_f32_e32 v105, v105, v109
	v_add_f32_e32 v109, 1.0, v114
	v_mul_f32_e32 v113, 0x3d372713, v111
	v_rcp_f32_e32 v109, v109
	v_mul_f32_e32 v113, v113, v111
	v_fma_f32 v113, v113, v111, v111
	v_mul_f32_e32 v113, 0x3fcc422a, v113
	v_cvt_pk_bf16_f32 v105, v105, v185
	v_mul_f32_e32 v113, 0xbfb8aa3b, v113
	v_exp_f32_e32 v113, v113
	ds_write_b16 v60, v105
	v_mul_f32_e32 v105, v109, v110
	s_waitcnt lgkmcnt(1)
	v_lshlrev_b32_e32 v109, 16, v112
	v_mul_f32_e32 v110, 0x3d372713, v109
	v_mul_f32_e32 v110, v110, v109
	v_add_f32_e32 v106, v106, v119
	v_fma_f32 v110, v110, v109, v109
	v_mul_f32_e32 v105, v106, v105
	v_add_f32_e32 v106, 1.0, v113
	v_mul_f32_e32 v110, 0x3fcc422a, v110
	v_rcp_f32_e32 v106, v106
	v_mul_f32_e32 v110, 0xbfb8aa3b, v110
	v_exp_f32_e32 v110, v110
	v_cvt_pk_bf16_f32 v105, v105, v185
	ds_write_b16 v60, v105 offset:128
	v_mul_f32_e32 v105, v106, v111
	v_add_f32_e32 v106, 1.0, v110
	v_mul_f32_e32 v46, v46, v105
	v_rcp_f32_e32 v106, v106
	v_cvt_pk_bf16_f32 v46, v46, v185
	ds_write_b16 v60, v46 offset:256
	ds_read_b32 v46, v55 offset:128
	v_mul_f32_e32 v105, v106, v109
	v_mul_f32_e32 v47, v47, v105
	s_and_b64 vcc, exec, s[48:49]
	v_cvt_pk_bf16_f32 v47, v47, v185
	ds_write_b16 v60, v47 offset:384
	s_cbranch_vccnz .LBB0_339
	s_waitcnt lgkmcnt(0)
	v_fmac_f32_e32 v151, v46, v150
	v_mov_b32_e32 v46, v151

; #define LAS __attribute__((address_space(3)))
; __device__ __forceinline__ unsigned pk2(float lo, float hi) { unsigned r; asm("v_cvt_pk_bf16_f32 %0, %1, %2" : "=v"(r) : "v"(lo), "v"(hi)); return r; }
; __device__ __forceinline__ float bflo(unsigned w) { return __uint_as_float(w << 16); }
; __device__ __forceinline__ float sigmoidf_(float v) { return __builtin_amdgcn_rcpf(1.0f + __expf(-v)); }
; __device__ __forceinline__ void scan_group(const Params& P, int l, int wgI, bool final_mode, bool with_ctx, LAS unsigned char* lds) {
;     ...
;             for (int eb = 0; eb < 4; ++eb) {
;                 const int c = eb * 16 + fr;
;                 float s = car[(0 * 9 + it) * 64 + c];
; #pragma unroll
;                 for (int v = 0; v < 7; ++v) { const f32x2 cv = wcomp[(0 * 8 + v) * 64 + c]; if (v < w) s = cv.x * s + cv.y; }
;                 s = Ae[0][eb] * s + Be[0][eb];
;                 float hf[4];
; #pragma unroll
;                 for (int j = 0; j < 4; ++j) { s = ca[0][eb][j] * s + cbv[0][eb][j]; hf[j] = s; }
;                 s = car[(1 * 9 + it) * 64 + c];
; #pragma unroll
;                 for (int v = 7; v > 0; --v) { const f32x2 cv = wcomp[(1 * 8 + v) * 64 + c]; if (v > w) s = cv.x * s + cv.y; }
;                 s = Ae[1][eb] * s + Be[1][eb];
; #pragma unroll
;                 for (int j = 3; j >= 0; --j) { s = ca[1][eb][j] * s + cbv[1][eb][j]; hf[j] += s; }
; #pragma unroll
;                 for (int j = 0; j < 4; ++j) {
;                     const int q = 16 * w + 4 * fq + j;
;                     const float g = bflo((unsigned)*(const LAS bf16_t*)(lds + SC_GL_OFF + q * 128 + c * 2));
;                     const float ge = g * sigmoidf_(1.5957691216f * (g + 0.044715f * g * g * g));
;                     *(LAS bf16_t*)(lds + SC_XC_OFF + q * 128 + c * 2) = (bf16_t)(pk2(hf[j] * ge, 0.f) & 0xffffu);
;                 }
.LBB0_352:
	ds_read_b64 v[150:151], v50 offset:43136
	ds_read_b64 v[152:153], v50 offset:43648
	ds_read_b64 v[154:155], v50 offset:44160
	ds_read_b64 v[156:157], v50 offset:44672
	ds_read_b64 v[158:159], v50 offset:45184
	ds_read_b64 v[160:161], v50 offset:45696
	ds_read_b64 v[162:163], v50 offset:46208
	ds_read_b64 v[164:165], v50 offset:50816
	ds_read_b64 v[166:167], v50 offset:50304
	ds_read_b64 v[168:169], v50 offset:49792
	ds_read_b64 v[170:171], v50 offset:49280
	ds_read_b64 v[172:173], v50 offset:48768
	ds_read_b64 v[174:175], v50 offset:48256
	ds_read_b64 v[176:177], v50 offset:47744
	v_cndmask_b32_e64 v95, v95, 1.0, s[44:45]
	v_cndmask_b32_e64 v96, v96, 0, s[44:45]
	s_waitcnt lgkmcnt(2)
	v_fmac_f32_e32 v96, v95, v46
	v_fmac_f32_e32 v85, v91, v96
	v_cndmask_b32_e64 v46, v107, 1.0, s[40:41]
	v_cndmask_b32_e64 v91, v108, 0, s[40:41]
	s_waitcnt lgkmcnt(0)
	v_fmac_f32_e32 v91, v46, v47
	v_fmac_f32_e32 v86, v92, v85
	v_fmac_f32_e32 v104, v103, v91
	v_fmac_f32_e32 v89, v93, v86
	v_fmac_f32_e32 v101, v102, v104
	v_fmac_f32_e32 v90, v94, v89
	v_add_f32_e32 v46, v89, v101
	ds_read_u16 v89, v61
	v_add_f32_e32 v47, v90, v104
	ds_read_u16 v90, v61 offset:128
	ds_read_u16 v91, v61 offset:256
	ds_read_u16 v92, v61 offset:384
	v_fmac_f32_e32 v99, v100, v101
	v_fmac_f32_e32 v98, v97, v99
	s_waitcnt lgkmcnt(3)
	v_lshlrev_b32_e32 v89, 16, v89
	v_mul_f32_e32 v93, 0x3d372713, v89
	v_mul_f32_e32 v93, v93, v89
	v_fma_f32 v93, v93, v89, v89
	v_mul_f32_e32 v93, 0x3fcc422a, v93
	v_mul_f32_e32 v93, 0xbfb8aa3b, v93
	v_exp_f32_e32 v93, v93
	s_waitcnt lgkmcnt(2)
	v_lshlrev_b32_e32 v90, 16, v90
	v_mul_f32_e32 v94, 0x3d372713, v90
	v_mul_f32_e32 v94, v94, v90
	v_fma_f32 v94, v94, v90, v90
	v_add_f32_e32 v93, 1.0, v93
	v_mul_f32_e32 v94, 0x3fcc422a, v94
	v_rcp_f32_e32 v93, v93
	v_mul_f32_e32 v94, 0xbfb8aa3b, v94
	v_exp_f32_e32 v94, v94
	v_add_f32_e32 v85, v85, v98
	v_mul_f32_e32 v89, v93, v89
	s_waitcnt lgkmcnt(1)
	v_lshlrev_b32_e32 v91, 16, v91
	v_mul_f32_e32 v85, v85, v89
	v_add_f32_e32 v89, 1.0, v94
	v_mul_f32_e32 v93, 0x3d372713, v91
	v_rcp_f32_e32 v89, v89
	v_mul_f32_e32 v93, v93, v91
	v_fma_f32 v93, v93, v91, v91
	v_mul_f32_e32 v93, 0x3fcc422a, v93
	v_cvt_pk_bf16_f32 v85, v85, v185
	v_mul_f32_e32 v93, 0xbfb8aa3b, v93
	v_exp_f32_e32 v93, v93
	ds_write_b16 v62, v85
	v_mul_f32_e32 v85, v89, v90
	s_waitcnt lgkmcnt(1)
	v_lshlrev_b32_e32 v89, 16, v92
	v_mul_f32_e32 v90, 0x3d372713, v89
	v_mul_f32_e32 v90, v90, v89
	v_add_f32_e32 v86, v86, v99
	v_fma_f32 v90, v90, v89, v89
	v_mul_f32_e32 v85, v86, v85
	v_add_f32_e32 v86, 1.0, v93
	v_mul_f32_e32 v90, 0x3fcc422a, v90
	v_rcp_f32_e32 v86, v86
	v_mul_f32_e32 v90, 0xbfb8aa3b, v90
	v_exp_f32_e32 v90, v90
	v_cvt_pk_bf16_f32 v85, v85, v185
	ds_write_b16 v62, v85 offset:128
	v_mul_f32_e32 v85, v86, v91
	v_add_f32_e32 v86, 1.0, v90
	v_mul_f32_e32 v46, v46, v85
	v_rcp_f32_e32 v86, v86
	v_cvt_pk_bf16_f32 v46, v46, v185
	ds_write_b16 v62, v46 offset:256
	ds_read_b32 v46, v55 offset:192
	v_mul_f32_e32 v85, v86, v89
	v_mul_f32_e32 v47, v47, v85
	s_and_b64 vcc, exec, s[48:49]
	v_cvt_pk_bf16_f32 v47, v47, v185
	ds_write_b16 v62, v47 offset:384
	s_cbranch_vccnz .LBB0_354
	s_waitcnt lgkmcnt(0)
	v_fmac_f32_e32 v151, v46, v150
	v_mov_b32_e32 v46, v151

; __device__ __forceinline__ void scan_group(const Params& P, int l, int wgI, bool final_mode, bool with_ctx, LAS unsigned char* lds) {
;     ...
;                 float s = car[(0 * 9 + it) * 64 + c];
; #pragma unroll
;                 for (int v = 0; v < 7; ++v) { const f32x2 cv = wcomp[(0 * 8 + v) * 64 + c]; if (v < w) s = cv.x * s + cv.y; }
;                 s = Ae[0][eb] * s + Be[0][eb];
;                 float hf[4];
; #pragma unroll
;                 for (int j = 0; j < 4; ++j) { s = ca[0][eb][j] * s + cbv[0][eb][j]; hf[j] = s; }
;                 s = car[(1 * 9 + it) * 64 + c];
; #pragma unroll
;                 for (int v = 7; v > 0; --v) { const f32x2 cv = wcomp[(1 * 8 + v) * 64 + c]; if (v > w) s = cv.x * s + cv.y; }
;                 s = Ae[1][eb] * s + Be[1][eb];
.LBB0_367:
	s_waitcnt lgkmcnt(0)
	v_fmac_f32_e32 v153, v46, v152
	v_mov_b32_e32 v46, v153
	v_cndmask_b32_e64 v47, 0, 1, s[6:7]
	v_cmp_ne_u32_e64 s[52:53], 1, v47
	s_andn2_b64 vcc, exec, s[6:7]
	s_cbranch_vccnz .LBB0_310
.LBB0_368:
	s_waitcnt lgkmcnt(0)
	v_fmac_f32_e32 v155, v46, v154
	v_mov_b32_e32 v46, v155
	v_cndmask_b32_e64 v47, 0, 1, s[14:15]
	v_cmp_ne_u32_e64 s[54:55], 1, v47
	s_andn2_b64 vcc, exec, s[14:15]
	s_cbranch_vccnz .LBB0_311
.LBB0_369:
	s_waitcnt lgkmcnt(0)
	v_fmac_f32_e32 v157, v46, v156
	v_mov_b32_e32 v46, v157
	v_cndmask_b32_e64 v47, 0, 1, s[16:17]
	v_cmp_ne_u32_e64 s[56:57], 1, v47
	s_andn2_b64 vcc, exec, s[16:17]
	s_cbranch_vccnz .LBB0_312
.LBB0_370:
	s_waitcnt lgkmcnt(0)
	v_fmac_f32_e32 v159, v46, v158
	v_mov_b32_e32 v46, v159
	v_cndmask_b32_e64 v47, 0, 1, s[18:19]
	v_cmp_ne_u32_e64 s[58:59], 1, v47
	s_andn2_b64 vcc, exec, s[18:19]
	s_cbranch_vccnz .LBB0_313
.LBB0_371:
	s_waitcnt lgkmcnt(0)
	v_fmac_f32_e32 v161, v46, v160
	v_mov_b32_e32 v46, v161
	v_cndmask_b32_e64 v47, 0, 1, s[20:21]
	v_cmp_ne_u32_e64 s[60:61], 1, v47
	s_andn2_b64 vcc, exec, s[20:21]
	s_cbranch_vccz .LBB0_314
	s_branch .LBB0_315
.LBB0_372:
	s_waitcnt lgkmcnt(0)
	v_fmac_f32_e32 v165, v47, v164
	v_mov_b32_e32 v47, v165
	v_cndmask_b32_e64 v147, 0, 1, s[24:25]
	v_cmp_ne_u32_e64 s[64:65], 1, v147
	s_andn2_b64 vcc, exec, s[24:25]
	s_cbranch_vccnz .LBB0_317
.LBB0_373:
	s_waitcnt lgkmcnt(0)
	v_fmac_f32_e32 v167, v47, v166
	v_mov_b32_e32 v47, v167
	v_cndmask_b32_e64 v147, 0, 1, s[26:27]
	v_cmp_ne_u32_e64 s[66:67], 1, v147
	s_andn2_b64 vcc, exec, s[26:27]
	s_cbranch_vccnz .LBB0_318
.LBB0_374:
	s_waitcnt lgkmcnt(0)
	v_fmac_f32_e32 v169, v47, v168
	v_mov_b32_e32 v47, v169
	v_cndmask_b32_e64 v147, 0, 1, s[28:29]
	v_cmp_ne_u32_e64 s[68:69], 1, v147
	s_andn2_b64 vcc, exec, s[28:29]
	s_cbranch_vccnz .LBB0_319
.LBB0_375:
	s_waitcnt lgkmcnt(0)
	v_fmac_f32_e32 v171, v47, v170
	v_mov_b32_e32 v47, v171
	v_cndmask_b32_e64 v147, 0, 1, s[30:31]
	v_cmp_ne_u32_e64 s[70:71], 1, v147
	s_andn2_b64 vcc, exec, s[30:31]
	s_cbranch_vccnz .LBB0_320
.LBB0_376:
	s_waitcnt lgkmcnt(0)
	v_fmac_f32_e32 v173, v47, v172
	v_mov_b32_e32 v47, v173
	v_cndmask_b32_e64 v147, 0, 1, s[34:35]
	v_cmp_ne_u32_e64 s[72:73], 1, v147
	s_andn2_b64 vcc, exec, s[34:35]
	s_cbranch_vccnz .LBB0_321
.LBB0_377:
	s_waitcnt lgkmcnt(0)
	v_fmac_f32_e32 v175, v47, v174
	v_mov_b32_e32 v47, v175
	v_cndmask_b32_e64 v147, 0, 1, s[36:37]
	v_cmp_ne_u32_e64 s[74:75], 1, v147
	s_andn2_b64 vcc, exec, s[36:37]
	s_cbranch_vccnz .LBB0_322
.LBB0_378:
	s_waitcnt lgkmcnt(0)
	v_fmac_f32_e32 v177, v47, v176
	v_mov_b32_e32 v47, v177
	s_branch .LBB0_322
.LBB0_379:
	s_waitcnt lgkmcnt(0)
	v_fmac_f32_e32 v153, v46, v152
	v_mov_b32_e32 v46, v153
	s_and_b64 vcc, exec, s[52:53]
	s_cbranch_vccnz .LBB0_326
.LBB0_380:
	s_waitcnt lgkmcnt(0)
	v_fmac_f32_e32 v155, v46, v154
	v_mov_b32_e32 v46, v155
	s_and_b64 vcc, exec, s[54:55]
	s_cbranch_vccnz .LBB0_327
.LBB0_381:
	s_waitcnt lgkmcnt(0)
	v_fmac_f32_e32 v157, v46, v156
	v_mov_b32_e32 v46, v157
	s_and_b64 vcc, exec, s[56:57]
	s_cbranch_vccnz .LBB0_328
.LBB0_382:
	s_waitcnt lgkmcnt(0)
	v_fmac_f32_e32 v159, v46, v158
	v_mov_b32_e32 v46, v159
	s_and_b64 vcc, exec, s[58:59]
	s_cbranch_vccnz .LBB0_329
.LBB0_383:
	s_waitcnt lgkmcnt(0)
	v_fmac_f32_e32 v161, v46, v160
	v_mov_b32_e32 v46, v161
	s_and_b64 vcc, exec, s[60:61]
	s_cbranch_vccnz .LBB0_330
.LBB0_384:
	s_waitcnt lgkmcnt(0)
	v_fmac_f32_e32 v163, v46, v162
	v_mov_b32_e32 v46, v163
	ds_read_b32 v47, v55 offset:2368
	s_and_b64 vcc, exec, s[62:63]
	s_cbranch_vccnz .LBB0_331
.LBB0_385:
	s_waitcnt lgkmcnt(0)
	v_fmac_f32_e32 v165, v47, v164
	v_mov_b32_e32 v47, v165
	s_and_b64 vcc, exec, s[64:65]
	s_cbranch_vccnz .LBB0_332
.LBB0_386:
	s_waitcnt lgkmcnt(0)
	v_fmac_f32_e32 v167, v47, v166
	v_mov_b32_e32 v47, v167
	s_and_b64 vcc, exec, s[66:67]
	s_cbranch_vccnz .LBB0_333
.LBB0_387:
	s_waitcnt lgkmcnt(0)
	v_fmac_f32_e32 v169, v47, v168
	v_mov_b32_e32 v47, v169
	s_and_b64 vcc, exec, s[68:69]
	s_cbranch_vccnz .LBB0_334
.LBB0_388:
	s_waitcnt lgkmcnt(0)
	v_fmac_f32_e32 v171, v47, v170
	v_mov_b32_e32 v47, v171
	s_and_b64 vcc, exec, s[70:71]
	s_cbranch_vccnz .LBB0_335
.LBB0_389:
	s_waitcnt lgkmcnt(0)
	v_fmac_f32_e32 v173, v47, v172
	v_mov_b32_e32 v47, v173
	s_and_b64 vcc, exec, s[72:73]
	s_cbranch_vccnz .LBB0_336
.LBB0_390:
	s_waitcnt lgkmcnt(0)
	v_fmac_f32_e32 v175, v47, v174
	v_mov_b32_e32 v47, v175
	s_and_b64 vcc, exec, s[74:75]
	s_cbranch_vccnz .LBB0_337

; __device__ __forceinline__ void scan_group(const Params& P, int l, int wgI, bool final_mode, bool with_ctx, LAS unsigned char* lds) {
;     ...
; #pragma unroll
;                 for (int v = 0; v < 7; ++v) { const f32x2 cv = wcomp[(0 * 8 + v) * 64 + c]; if (v < w) s = cv.x * s + cv.y; }
;                 s = Ae[0][eb] * s + Be[0][eb];
;                 float hf[4];
; #pragma unroll
;                 for (int j = 0; j < 4; ++j) { s = ca[0][eb][j] * s + cbv[0][eb][j]; hf[j] = s; }
;                 s = car[(1 * 9 + it) * 64 + c];
; #pragma unroll
;                 for (int v = 7; v > 0; --v) { const f32x2 cv = wcomp[(1 * 8 + v) * 64 + c]; if (v > w) s = cv.x * s + cv.y; }
.LBB0_397:
	s_waitcnt lgkmcnt(0)
	v_fmac_f32_e32 v163, v46, v162
	v_mov_b32_e32 v46, v163
	ds_read_b32 v47, v55 offset:2432
	s_and_b64 vcc, exec, s[62:63]
	s_cbranch_vccnz .LBB0_346

; __device__ __forceinline__ void scan_group(const Params& P, int l, int wgI, bool final_mode, bool with_ctx, LAS unsigned char* lds) {
;     ...
; #pragma unroll
;                 for (int v = 0; v < 7; ++v) { const f32x2 cv = wcomp[(0 * 8 + v) * 64 + c]; if (v < w) s = cv.x * s + cv.y; }
;                 s = Ae[0][eb] * s + Be[0][eb];
;                 float hf[4];
; #pragma unroll
;                 for (int j = 0; j < 4; ++j) { s = ca[0][eb][j] * s + cbv[0][eb][j]; hf[j] = s; }
;                 s = car[(1 * 9 + it) * 64 + c];
; #pragma unroll
;                 for (int v = 7; v > 0; --v) { const f32x2 cv = wcomp[(1 * 8 + v) * 64 + c]; if (v > w) s = cv.x * s + cv.y; }
.LBB0_409:
	s_waitcnt lgkmcnt(0)
	v_fmac_f32_e32 v161, v46, v160
	v_mov_b32_e32 v46, v161
	s_mov_b32 s59, s2
	s_and_b64 vcc, exec, s[60:61]
	s_cbranch_vccnz .LBB0_360
.LBB0_410:
	s_waitcnt lgkmcnt(0)
	v_fmac_f32_e32 v163, v46, v162
	v_mov_b32_e32 v46, v163
	ds_read_b32 v47, v55 offset:2496
	s_and_b64 vcc, exec, s[62:63]
	s_cbranch_vccnz .LBB0_361
